# attn PV accumulators ping-pong between the two unrolled half-iterations: 32 v_mov_b64 copies per tile removed
# speedup vs baseline: 1.0226x; 1.0226x over previous
.LBB0_854:
	s_cmp_ge_u32 s90, s85
	s_mov_b64 s[0:1], -1
	s_cbranch_scc0 .LBB0_856
	ds_read_b64_tr_b16 v[132:133], v215 offset:17408
	ds_read_b64_tr_b16 v[136:137], v215 offset:17440
	ds_read_b64_tr_b16 v[140:141], v215 offset:17472
	ds_read_b64_tr_b16 v[144:145], v215 offset:17504
	ds_read_b64_tr_b16 v[134:135], v215 offset:22016
	ds_read_b64_tr_b16 v[138:139], v215 offset:22048
	ds_read_b64_tr_b16 v[142:143], v215 offset:22080
	ds_read_b64_tr_b16 v[146:147], v215 offset:22112
	s_waitcnt lgkmcnt(3)
	v_mfma_f32_16x16x32_bf16 v[148:151], v[36:39], v[132:135], v[128:131]
	v_mfma_f32_16x16x32_bf16 v[132:135], v[60:63], v[132:135], v[120:123]
	s_waitcnt lgkmcnt(2)
	v_mfma_f32_16x16x32_bf16 v[152:155], v[36:39], v[136:139], v[124:127]
	v_mfma_f32_16x16x32_bf16 v[136:139], v[60:63], v[136:139], v[108:111]
	s_waitcnt lgkmcnt(1)
	v_mfma_f32_16x16x32_bf16 v[156:159], v[36:39], v[140:143], v[116:119]
	v_mfma_f32_16x16x32_bf16 v[160:163], v[60:63], v[140:143], v[100:103]
	s_waitcnt lgkmcnt(0)
	v_mfma_f32_16x16x32_bf16 v[164:167], v[36:39], v[144:147], v[104:107]
	v_mfma_f32_16x16x32_bf16 v[168:171], v[60:63], v[144:147], v[96:99]
	ds_read_b64_tr_b16 v[140:141], v215 offset:17536
	ds_read_b64_tr_b16 v[144:145], v215 offset:17568
	ds_read_b64_tr_b16 v[172:173], v215 offset:17600
	ds_read_b64_tr_b16 v[176:177], v215 offset:17632
	ds_read_b64_tr_b16 v[142:143], v215 offset:22144
	ds_read_b64_tr_b16 v[146:147], v215 offset:22176
	ds_read_b64_tr_b16 v[174:175], v215 offset:22208
	ds_read_b64_tr_b16 v[178:179], v215 offset:22240
	s_waitcnt lgkmcnt(3)
	v_mfma_f32_16x16x32_bf16 v[180:183], v[36:39], v[140:143], v[88:91]
	v_mfma_f32_16x16x32_bf16 v[184:187], v[60:63], v[140:143], v[76:79]
	s_waitcnt lgkmcnt(2)
	v_mfma_f32_16x16x32_bf16 v[188:191], v[36:39], v[144:147], v[80:83]
	v_mfma_f32_16x16x32_bf16 v[192:195], v[60:63], v[144:147], v[64:67]
	s_waitcnt lgkmcnt(1)
	v_mfma_f32_16x16x32_bf16 v[218:221], v[36:39], v[172:175], v[68:71]
	v_mfma_f32_16x16x32_bf16 v[222:225], v[60:63], v[172:175], v[52:55]
	s_waitcnt lgkmcnt(0)
	v_mfma_f32_16x16x32_bf16 v[226:229], v[36:39], v[176:179], v[56:59]
	v_mfma_f32_16x16x32_bf16 v[230:233], v[60:63], v[176:179], v[48:51]
	ds_read_b64_tr_b16 v[140:141], v215 offset:26624
	ds_read_b64_tr_b16 v[172:173], v215 offset:26656
	ds_read_b64_tr_b16 v[176:177], v215 offset:26688
	ds_read_b64_tr_b16 v[234:235], v215 offset:26720
	ds_read_b64_tr_b16 v[142:143], v215 offset:31232
	ds_read_b64_tr_b16 v[174:175], v215 offset:31264
	ds_read_b64_tr_b16 v[178:179], v215 offset:31296
	ds_read_b64_tr_b16 v[236:237], v215 offset:31328
	s_waitcnt lgkmcnt(3)
	v_mfma_f32_16x16x32_bf16 v[144:147], v[40:43], v[140:143], v[148:151]
	v_mfma_f32_16x16x32_bf16 v[140:143], v[84:87], v[140:143], v[132:135]
	s_waitcnt lgkmcnt(2)
	v_mfma_f32_16x16x32_bf16 v[148:151], v[40:43], v[172:175], v[152:155]
	v_mfma_f32_16x16x32_bf16 v[136:139], v[84:87], v[172:175], v[136:139]
	s_waitcnt lgkmcnt(1)
	v_mfma_f32_16x16x32_bf16 v[156:159], v[40:43], v[176:179], v[156:159]
	v_mfma_f32_16x16x32_bf16 v[152:155], v[84:87], v[176:179], v[160:163]
	s_waitcnt lgkmcnt(0)
	v_mfma_f32_16x16x32_bf16 v[164:167], v[40:43], v[234:237], v[164:167]
	v_mfma_f32_16x16x32_bf16 v[160:163], v[84:87], v[234:237], v[168:171]
	ds_read_b64_tr_b16 v[132:133], v215 offset:26752
	ds_read_b64_tr_b16 v[234:235], v215 offset:26784
	ds_read_b64_tr_b16 v[238:239], v215 offset:26816
	ds_read_b64_tr_b16 v[242:243], v215 offset:26848
	ds_read_b64_tr_b16 v[134:135], v215 offset:31360
	ds_read_b64_tr_b16 v[236:237], v215 offset:31392
	ds_read_b64_tr_b16 v[240:241], v215 offset:31424
	ds_read_b64_tr_b16 v[244:245], v215 offset:31456
	s_waitcnt lgkmcnt(3)
	v_mfma_f32_16x16x32_bf16 v[172:175], v[40:43], v[132:135], v[180:183]
	v_mfma_f32_16x16x32_bf16 v[168:171], v[84:87], v[132:135], v[184:187]
	s_waitcnt lgkmcnt(2)
	v_mfma_f32_16x16x32_bf16 v[176:179], v[40:43], v[234:237], v[188:191]
	v_mfma_f32_16x16x32_bf16 v[132:135], v[84:87], v[234:237], v[192:195]
	s_waitcnt lgkmcnt(1)
	v_mfma_f32_16x16x32_bf16 v[184:187], v[40:43], v[238:241], v[218:221]
	v_mfma_f32_16x16x32_bf16 v[180:183], v[84:87], v[238:241], v[222:225]
	s_waitcnt lgkmcnt(0)
	v_mfma_f32_16x16x32_bf16 v[192:195], v[40:43], v[242:245], v[226:229]
	v_mfma_f32_16x16x32_bf16 v[188:191], v[84:87], v[242:245], v[230:233]
	s_mov_b64 s[0:1], 0
	s_nop 7
	v_mov_b64_e32 v[128:129], v[144:145]
	v_mov_b64_e32 v[124:125], v[148:149]
	v_mov_b64_e32 v[116:117], v[156:157]
	v_mov_b64_e32 v[104:105], v[164:165]
	v_mov_b64_e32 v[88:89], v[172:173]
	v_mov_b64_e32 v[80:81], v[176:177]
	v_mov_b64_e32 v[68:69], v[184:185]
	v_mov_b64_e32 v[56:57], v[192:193]
	v_mov_b64_e32 v[120:121], v[140:141]
	v_mov_b64_e32 v[108:109], v[136:137]
	v_mov_b64_e32 v[100:101], v[152:153]
	v_mov_b64_e32 v[96:97], v[160:161]
	v_mov_b64_e32 v[76:77], v[168:169]
	v_mov_b64_e32 v[64:65], v[132:133]
	v_mov_b64_e32 v[52:53], v[180:181]
	v_mov_b64_e32 v[48:49], v[188:189]
	v_mov_b64_e32 v[130:131], v[146:147]
	v_mov_b64_e32 v[126:127], v[150:151]
	v_mov_b64_e32 v[118:119], v[158:159]
	v_mov_b64_e32 v[106:107], v[166:167]
	v_mov_b64_e32 v[90:91], v[174:175]
	v_mov_b64_e32 v[82:83], v[178:179]
	v_mov_b64_e32 v[70:71], v[186:187]
	v_mov_b64_e32 v[58:59], v[194:195]
	v_mov_b64_e32 v[122:123], v[142:143]
	v_mov_b64_e32 v[110:111], v[138:139]
	v_mov_b64_e32 v[102:103], v[154:155]
	v_mov_b64_e32 v[98:99], v[162:163]
	v_mov_b64_e32 v[78:79], v[170:171]
	v_mov_b64_e32 v[66:67], v[134:135]
	v_mov_b64_e32 v[54:55], v[182:183]
	v_mov_b64_e32 v[50:51], v[190:191]

; #define LAS __attribute__((address_space(3)))
; #define EXPALL(PF) do { _Pragma("unroll") for (int s_ = 0; s_ < 16 * NQT; ++s_) EXP1(s_); PACK16(PF, 0, 0); PACK16(PF, 0, 1); if (NQT > 1) { PACK16(PF, 1, 0); PACK16(PF, 1, 1); } } while (0)
; template <bool SAMPLE> __device__ __forceinline__ void attn_unit16(const Ctx& c, LAS unsigned char* lds, int b, int h, int qb, int wave_s) {
;     ...
;     if (SAMPLE) { load_kv(0, true); load_kv(0, false); store_k(0); store_v(0); load_kv(1, true); store_k(1); }
;     else { load_kv(0, true); const u32x4 k0a = kreg[0], k0b = kreg[1];
;       load_kv(0, false); load_kv(1, true);
;       LAS unsigned char* kb0 = lds + lrow * A_RSK + lck * 16; *(LAS u32x4*)kb0 = k0a; *(LAS u32x4*)(kb0 + 128) = k0b;
;       store_v(0); store_k(1); }
;     __syncthreads();
;     if (active) { QK16(0); MAX16(0); EXPALL(pfa); }
;     for (int j = 0; j < ntiles; j += 2) {
;         ITER16(j, pfa, pfb, 0, 1);
;         if (j + 1 < ntiles) ITER16(j + 1, pfb, pfa, 1, 0);
.LBB0_866:
	v_cndmask_b32_e64 v0, 0, 1, s[2:3]
	v_cmp_ne_u32_e64 s[0:1], 1, v0
	s_andn2_b64 vcc, exec, s[2:3]
	s_cbranch_vccnz .LBB0_841

.LBB0_870:
	s_cmp_ge_u32 s89, s83
	s_mov_b64 s[2:3], -1
	s_cbranch_scc0 .LBB0_872
	ds_read_b64_tr_b16 v[64:65], v215 offset:53248
	ds_read_b64_tr_b16 v[108:109], v215 offset:53280
	ds_read_b64_tr_b16 v[120:121], v215 offset:53312
	ds_read_b64_tr_b16 v[128:129], v215 offset:53344
	ds_read_b64_tr_b16 v[66:67], v215 offset:57856
	ds_read_b64_tr_b16 v[110:111], v215 offset:57888
	ds_read_b64_tr_b16 v[122:123], v215 offset:57920
	ds_read_b64_tr_b16 v[130:131], v215 offset:57952
	s_waitcnt lgkmcnt(3)
	v_mfma_f32_16x16x32_bf16 v[124:127], v[44:47], v[64:67], v[144:147]
	v_mfma_f32_16x16x32_bf16 v[64:67], v[92:95], v[64:67], v[140:143]
	s_waitcnt lgkmcnt(2)
	v_mfma_f32_16x16x32_bf16 v[100:103], v[44:47], v[108:111], v[148:151]
	v_mfma_f32_16x16x32_bf16 v[108:111], v[92:95], v[108:111], v[136:139]
	s_waitcnt lgkmcnt(1)
	v_mfma_f32_16x16x32_bf16 v[116:119], v[44:47], v[120:123], v[156:159]
	v_mfma_f32_16x16x32_bf16 v[96:99], v[92:95], v[120:123], v[152:155]
	s_waitcnt lgkmcnt(0)
	v_mfma_f32_16x16x32_bf16 v[104:107], v[44:47], v[128:131], v[164:167]
	v_mfma_f32_16x16x32_bf16 v[76:79], v[92:95], v[128:131], v[160:163]
	ds_read_b64_tr_b16 v[120:121], v215 offset:53376
	ds_read_b64_tr_b16 v[128:129], v215 offset:53408
	ds_read_b64_tr_b16 v[88:89], v215 offset:53440
	ds_read_b64_tr_b16 v[80:81], v215 offset:53472
	ds_read_b64_tr_b16 v[122:123], v215 offset:57984
	ds_read_b64_tr_b16 v[130:131], v215 offset:58016
	ds_read_b64_tr_b16 v[90:91], v215 offset:58048
	ds_read_b64_tr_b16 v[82:83], v215 offset:58080
	s_waitcnt lgkmcnt(3)
	v_mfma_f32_16x16x32_bf16 v[52:55], v[44:47], v[120:123], v[172:175]
	v_mfma_f32_16x16x32_bf16 v[68:71], v[92:95], v[120:123], v[168:171]
	s_waitcnt lgkmcnt(2)
	v_mfma_f32_16x16x32_bf16 v[48:51], v[44:47], v[128:131], v[176:179]
	v_mfma_f32_16x16x32_bf16 v[56:59], v[92:95], v[128:131], v[132:135]
	s_waitcnt lgkmcnt(1)
	v_mfma_f32_16x16x32_bf16 v[218:221], v[44:47], v[88:91], v[184:187]
	v_mfma_f32_16x16x32_bf16 v[222:225], v[92:95], v[88:91], v[180:183]
	s_waitcnt lgkmcnt(0)
	v_mfma_f32_16x16x32_bf16 v[226:229], v[44:47], v[80:83], v[192:195]
	v_mfma_f32_16x16x32_bf16 v[230:233], v[92:95], v[80:83], v[188:191]
	ds_read_b64_tr_b16 v[120:121], v215 offset:62464
	ds_read_b64_tr_b16 v[88:89], v215 offset:62496
	ds_read_b64_tr_b16 v[80:81], v215 offset:62528
	ds_read_b64_tr_b16 v[234:235], v215 offset:62560
	ds_read_b64_tr_b16 v[122:123], v216 offset:13824
	ds_read_b64_tr_b16 v[90:91], v216 offset:13856
	ds_read_b64_tr_b16 v[82:83], v216 offset:13888
	ds_read_b64_tr_b16 v[236:237], v216 offset:13920
	s_waitcnt lgkmcnt(3)
	v_mfma_f32_16x16x32_bf16 v[128:131], v[72:75], v[120:123], v[124:127]
	v_mfma_f32_16x16x32_bf16 v[120:123], v[112:115], v[120:123], v[64:67]
	s_waitcnt lgkmcnt(2)
	v_mfma_f32_16x16x32_bf16 v[124:127], v[72:75], v[88:91], v[100:103]
	v_mfma_f32_16x16x32_bf16 v[108:111], v[112:115], v[88:91], v[108:111]
	s_waitcnt lgkmcnt(1)
	v_mfma_f32_16x16x32_bf16 v[116:119], v[72:75], v[80:83], v[116:119]
	v_mfma_f32_16x16x32_bf16 v[100:103], v[112:115], v[80:83], v[96:99]
	s_waitcnt lgkmcnt(0)
	v_mfma_f32_16x16x32_bf16 v[104:107], v[72:75], v[234:237], v[104:107]
	v_mfma_f32_16x16x32_bf16 v[96:99], v[112:115], v[234:237], v[76:79]
	ds_read_b64_tr_b16 v[64:65], v215 offset:62592
	ds_read_b64_tr_b16 v[234:235], v215 offset:62624
	ds_read_b64_tr_b16 v[238:239], v215 offset:62656
	ds_read_b64_tr_b16 v[242:243], v215 offset:62688
	ds_read_b64_tr_b16 v[66:67], v216 offset:13952
	ds_read_b64_tr_b16 v[236:237], v216 offset:13984
	ds_read_b64_tr_b16 v[240:241], v216 offset:14016
	ds_read_b64_tr_b16 v[244:245], v216 offset:14048
	s_waitcnt lgkmcnt(3)
	v_mfma_f32_16x16x32_bf16 v[88:91], v[72:75], v[64:67], v[52:55]
	v_mfma_f32_16x16x32_bf16 v[76:79], v[112:115], v[64:67], v[68:71]
	s_waitcnt lgkmcnt(2)
	v_mfma_f32_16x16x32_bf16 v[80:83], v[72:75], v[234:237], v[48:51]
	v_mfma_f32_16x16x32_bf16 v[64:67], v[112:115], v[234:237], v[56:59]
	s_waitcnt lgkmcnt(1)
	v_mfma_f32_16x16x32_bf16 v[68:71], v[72:75], v[238:241], v[218:221]
	v_mfma_f32_16x16x32_bf16 v[52:55], v[112:115], v[238:241], v[222:225]
	s_waitcnt lgkmcnt(0)
	v_mfma_f32_16x16x32_bf16 v[56:59], v[72:75], v[242:245], v[226:229]
	v_mfma_f32_16x16x32_bf16 v[48:51], v[112:115], v[242:245], v[230:233]
	s_mov_b64 s[2:3], 0
.LBB0_872:
	s_andn2_b64 vcc, exec, s[2:3]
	s_cbranch_vccnz .LBB0_882
	ds_read_b128 v[36:39], v214
	ds_read_b128 v[40:43], v214 offset:64
	ds_read_b128 v[60:63], v214 offset:4352
	ds_read_b128 v[84:87], v214 offset:4416
	ds_read_b128 v[64:67], v214 offset:8704
	ds_read_b128 v[124:127], v214 offset:8768
	ds_read_b128 v[108:111], v214 offset:13056
	ds_read_b128 v[100:103], v214 offset:13120
	s_waitcnt lgkmcnt(7)
	v_mfma_f32_16x16x32_bf16 v[120:123], v[36:39], v[8:11], 0
	v_mfma_f32_16x16x32_bf16 v[36:39], v[36:39], v[20:23], 0
	s_waitcnt lgkmcnt(5)
	v_mfma_f32_16x16x32_bf16 v[116:119], v[60:63], v[8:11], 0
	v_mfma_f32_16x16x32_bf16 v[60:63], v[60:63], v[20:23], 0
	s_waitcnt lgkmcnt(3)
	v_mfma_f32_16x16x32_bf16 v[96:99], v[64:67], v[8:11], 0
	v_mfma_f32_16x16x32_bf16 v[64:67], v[64:67], v[20:23], 0
	s_waitcnt lgkmcnt(1)
	v_mfma_f32_16x16x32_bf16 v[104:107], v[108:111], v[8:11], 0
	v_mfma_f32_16x16x32_bf16 v[76:79], v[108:111], v[20:23], 0
	v_mfma_f32_16x16x32_bf16 v[128:131], v[40:43], v[16:19], v[120:123]
	v_mfma_f32_16x16x32_bf16 v[108:111], v[40:43], v[24:27], v[36:39]
	v_mfma_f32_16x16x32_bf16 v[36:39], v[84:87], v[16:19], v[116:119]
	v_mfma_f32_16x16x32_bf16 v[60:63], v[84:87], v[24:27], v[60:63]
	v_mfma_f32_16x16x32_bf16 v[120:123], v[124:127], v[16:19], v[96:99]
	v_mfma_f32_16x16x32_bf16 v[64:67], v[124:127], v[24:27], v[64:67]
	s_waitcnt lgkmcnt(0)
	v_mfma_f32_16x16x32_bf16 v[40:43], v[100:103], v[16:19], v[104:107]
	v_mfma_f32_16x16x32_bf16 v[84:87], v[100:103], v[24:27], v[76:79]
	v_cmp_neq_f32_e32 vcc, 0, v196
	v_cmp_neq_f32_e64 s[2:3], 0, v197
	s_or_b64 vcc, vcc, s[2:3]
	s_cbranch_vccz .LBB0_875
	v_sub_f32_e32 v131, v131, v196
	v_sub_f32_e32 v130, v130, v196
	v_sub_f32_e32 v129, v129, v196
	v_sub_f32_e32 v128, v128, v196
	v_sub_f32_e32 v39, v39, v196
	v_sub_f32_e32 v38, v38, v196
	v_sub_f32_e32 v37, v37, v196
	v_sub_f32_e32 v36, v36, v196
	v_sub_f32_e32 v123, v123, v196
	v_sub_f32_e32 v122, v122, v196
	v_sub_f32_e32 v121, v121, v196
	v_sub_f32_e32 v120, v120, v196
	v_sub_f32_e32 v43, v43, v196
	v_sub_f32_e32 v42, v42, v196
	v_sub_f32_e32 v41, v41, v196
	v_sub_f32_e32 v40, v40, v196
	v_sub_f32_e32 v111, v111, v197
	v_sub_f32_e32 v110, v110, v197
	v_sub_f32_e32 v109, v109, v197
	v_sub_f32_e32 v108, v108, v197
	v_sub_f32_e32 v63, v63, v197
	v_sub_f32_e32 v62, v62, v197
	v_sub_f32_e32 v61, v61, v197
	v_sub_f32_e32 v60, v60, v197
	v_sub_f32_e32 v67, v67, v197
	v_sub_f32_e32 v66, v66, v197
	v_sub_f32_e32 v65, v65, v197
	v_sub_f32_e32 v64, v64, v197
	v_sub_f32_e32 v87, v87, v197
	v_sub_f32_e32 v86, v86, v197
	v_sub_f32_e32 v85, v85, v197
	v_sub_f32_e32 v84, v84, v197
.LBB0_875:
	s_add_i32 s2, s87, 64
	s_cmp_le_u32 s2, s86
	s_cbranch_scc1 .LBB0_877
	v_add_u32_e32 v0, s87, v217
	v_add_u32_e32 v102, 0xc0, v0
	v_max_i32_e32 v3, -1, v102
	v_max_i32_e32 v124, -2, v102
	v_max_i32_e32 v125, -3, v102
	v_max_i32_e32 v126, -16, v102
	v_max_i32_e32 v127, 0xffffffef, v102
	v_max_i32_e32 v100, 0xffffffee, v102
	v_max_i32_e32 v101, 0xffffffed, v102
	v_add_u32_e32 v3, 1, v3
	v_add_u32_e32 v124, 2, v124
	v_add_u32_e32 v125, 3, v125
	v_add_u32_e32 v126, 16, v126
	v_add_u32_e32 v127, 17, v127
	v_add_u32_e32 v100, 18, v100
	v_add_u32_e32 v101, 19, v101
	v_med3_i32 v2, v102, 0, v209
	v_min_u32_e32 v3, 0xff, v3
	v_min_u32_e32 v124, 0xff, v124
	v_min_u32_e32 v125, 0xff, v125
	v_min_u32_e32 v126, 0xff, v126
	v_min_u32_e32 v127, 0xff, v127
	v_min_u32_e32 v100, 0xff, v100
	v_min_u32_e32 v101, 0xff, v101
	v_lshl_add_u32 v2, v2, 2, s71
	v_lshl_add_u32 v3, v3, 2, s71
	v_lshl_add_u32 v124, v124, 2, s71
	v_lshl_add_u32 v125, v125, 2, s71
	v_lshl_add_u32 v126, v126, 2, s71
	v_lshl_add_u32 v127, v127, 2, s71
	v_lshl_add_u32 v100, v100, 2, s71
	v_lshl_add_u32 v101, v101, 2, s71
	ds_read_b32 v2, v2
	ds_read_b32 v3, v3
	ds_read_b32 v124, v124
	ds_read_b32 v125, v125
	ds_read_b32 v126, v126
	ds_read_b32 v127, v127
	ds_read_b32 v100, v100
	ds_read_b32 v101, v101
	s_waitcnt lgkmcnt(4)
	v_pk_add_f32 v[130:131], v[130:131], v[124:125]
	v_pk_add_f32 v[128:129], v[128:129], v[2:3]
	v_max_i32_e32 v2, 0xffffffe0, v102
	v_max_i32_e32 v3, 0xffffffdf, v102
	v_max_i32_e32 v124, 0xffffffde, v102
	v_max_i32_e32 v125, 0xffffffdd, v102
	v_max_i32_e32 v103, 0xffffffd0, v102
	v_max_i32_e32 v116, 0xffffffcf, v102
	v_max_i32_e32 v117, 0xffffffce, v102
	v_add_u32_e32 v2, 32, v2
	v_add_u32_e32 v3, 33, v3
	v_add_u32_e32 v124, 34, v124
	v_add_u32_e32 v125, 35, v125
	v_add_u32_e32 v103, 48, v103
	v_add_u32_e32 v116, 49, v116
	v_add_u32_e32 v117, 50, v117
	v_max_i32_e32 v102, 0xffffffcd, v102
	v_min_u32_e32 v2, 0xff, v2
	v_min_u32_e32 v3, 0xff, v3
	v_min_u32_e32 v124, 0xff, v124
	v_min_u32_e32 v125, 0xff, v125
	v_min_u32_e32 v103, 0xff, v103
	v_min_u32_e32 v116, 0xff, v116
	v_min_u32_e32 v117, 0xff, v117
	v_add_u32_e32 v102, 51, v102
	v_lshl_add_u32 v2, v2, 2, s71
	v_lshl_add_u32 v3, v3, 2, s71
	v_lshl_add_u32 v124, v124, 2, s71
	v_lshl_add_u32 v125, v125, 2, s71
	v_lshl_add_u32 v103, v103, 2, s71
	v_lshl_add_u32 v116, v116, 2, s71
	v_lshl_add_u32 v117, v117, 2, s71
	v_min_u32_e32 v102, 0xff, v102
	v_lshl_add_u32 v118, v102, 2, s71
	ds_read_b32 v2, v2
	ds_read_b32 v3, v3
	ds_read_b32 v124, v124
	ds_read_b32 v125, v125
	ds_read_b32 v102, v103
	ds_read_b32 v103, v116
	ds_read_b32 v116, v117
	ds_read_b32 v117, v118
	v_add_u32_e32 v0, 0xb0, v0
	s_waitcnt lgkmcnt(8)
	v_pk_add_f32 v[38:39], v[38:39], v[100:101]
	v_pk_add_f32 v[36:37], v[36:37], v[126:127]
	s_waitcnt lgkmcnt(4)
	v_pk_add_f32 v[122:123], v[122:123], v[124:125]
	v_pk_add_f32 v[120:121], v[120:121], v[2:3]
	v_max_i32_e32 v3, -1, v0
	v_max_i32_e32 v124, -2, v0
	v_max_i32_e32 v125, -3, v0
	v_max_i32_e32 v126, -16, v0
	v_max_i32_e32 v127, 0xffffffef, v0
	v_max_i32_e32 v100, 0xffffffee, v0
	v_max_i32_e32 v101, 0xffffffed, v0
	v_add_u32_e32 v3, 1, v3
	v_add_u32_e32 v124, 2, v124
	v_add_u32_e32 v125, 3, v125
	v_add_u32_e32 v126, 16, v126
	v_add_u32_e32 v127, 17, v127
	v_add_u32_e32 v100, 18, v100
	v_add_u32_e32 v101, 19, v101
	v_med3_i32 v2, v0, 0, v209
	v_min_u32_e32 v3, 0xff, v3
	v_min_u32_e32 v124, 0xff, v124
	v_min_u32_e32 v125, 0xff, v125
	v_min_u32_e32 v126, 0xff, v126
	v_min_u32_e32 v127, 0xff, v127
	v_min_u32_e32 v100, 0xff, v100
	v_min_u32_e32 v101, 0xff, v101
	v_lshl_add_u32 v2, v2, 2, s71
	v_lshl_add_u32 v3, v3, 2, s71
	v_lshl_add_u32 v124, v124, 2, s71
	v_lshl_add_u32 v125, v125, 2, s71
	v_lshl_add_u32 v126, v126, 2, s71
	v_lshl_add_u32 v127, v127, 2, s71
	v_lshl_add_u32 v100, v100, 2, s71
	v_lshl_add_u32 v101, v101, 2, s71
	ds_read_b32 v2, v2
	ds_read_b32 v3, v3
	ds_read_b32 v124, v124
	ds_read_b32 v125, v125
	ds_read_b32 v126, v126
	ds_read_b32 v127, v127
	ds_read_b32 v100, v100
	ds_read_b32 v101, v101
	s_waitcnt lgkmcnt(8)
	v_pk_add_f32 v[42:43], v[42:43], v[116:117]
	v_pk_add_f32 v[40:41], v[40:41], v[102:103]
	s_waitcnt lgkmcnt(4)
	v_pk_add_f32 v[110:111], v[110:111], v[124:125]
	v_pk_add_f32 v[108:109], v[108:109], v[2:3]
	v_max_i32_e32 v2, 0xffffffe0, v0
	v_max_i32_e32 v3, 0xffffffdf, v0
	v_max_i32_e32 v124, 0xffffffde, v0
	v_max_i32_e32 v125, 0xffffffdd, v0
	v_max_i32_e32 v102, 0xffffffd0, v0
	v_max_i32_e32 v103, 0xffffffcf, v0
	v_max_i32_e32 v116, 0xffffffce, v0
	v_add_u32_e32 v2, 32, v2
	v_add_u32_e32 v3, 33, v3
	v_add_u32_e32 v124, 34, v124
	v_add_u32_e32 v125, 35, v125
	v_add_u32_e32 v102, 48, v102
	v_add_u32_e32 v103, 49, v103
	v_add_u32_e32 v116, 50, v116
	v_max_i32_e32 v0, 0xffffffcd, v0
	v_min_u32_e32 v2, 0xff, v2
	v_min_u32_e32 v3, 0xff, v3
	v_min_u32_e32 v124, 0xff, v124
	v_min_u32_e32 v125, 0xff, v125
	v_min_u32_e32 v102, 0xff, v102
	v_min_u32_e32 v103, 0xff, v103
	v_min_u32_e32 v116, 0xff, v116
	v_add_u32_e32 v0, 51, v0
	v_lshl_add_u32 v2, v2, 2, s71
	v_lshl_add_u32 v3, v3, 2, s71
	v_lshl_add_u32 v124, v124, 2, s71
	v_lshl_add_u32 v125, v125, 2, s71
	v_lshl_add_u32 v102, v102, 2, s71
	v_lshl_add_u32 v103, v103, 2, s71
	v_lshl_add_u32 v116, v116, 2, s71
	v_min_u32_e32 v0, 0xff, v0
	v_lshl_add_u32 v0, v0, 2, s71
	ds_read_b32 v2, v2
	ds_read_b32 v3, v3
	ds_read_b32 v124, v124
	ds_read_b32 v125, v125
	ds_read_b32 v102, v102
	ds_read_b32 v103, v103
	ds_read_b32 v116, v116
	ds_read_b32 v117, v0
	s_waitcnt lgkmcnt(8)
	v_pk_add_f32 v[62:63], v[62:63], v[100:101]
	v_pk_add_f32 v[60:61], v[60:61], v[126:127]
	s_waitcnt lgkmcnt(4)
	v_pk_add_f32 v[66:67], v[66:67], v[124:125]
	v_pk_add_f32 v[64:65], v[64:65], v[2:3]
	s_waitcnt lgkmcnt(0)
	v_pk_add_f32 v[86:87], v[86:87], v[116:117]
	v_pk_add_f32 v[84:85], v[84:85], v[102:103]
.LBB0_877:
	v_max_f32_e32 v0, v129, v129
	v_max_f32_e32 v2, v128, v128
	v_max_f32_e32 v0, v2, v0
	v_max3_f32 v2, v131, v36, v37
	v_max3_f32 v0, v0, v130, v38
	v_max3_f32 v2, v2, v120, v121
	v_max3_f32 v0, v0, v39, v122
	v_max3_f32 v2, v2, v40, v41
	v_max3_f32 v0, v0, v123, v42
	v_max3_f32 v0, v0, v43, v2
	v_max_f32_e32 v2, v109, v109
	v_max_f32_e32 v3, v108, v108
	v_max_f32_e32 v2, v3, v2
	v_max3_f32 v3, v111, v60, v61
	v_max3_f32 v2, v2, v110, v62
	v_max3_f32 v3, v3, v64, v65
	v_max3_f32 v2, v2, v63, v66
	v_max3_f32 v3, v3, v84, v85
	v_max3_f32 v2, v2, v67, v86
	v_max3_f32 v2, v2, v87, v3
	v_max_f32_e32 v3, v0, v2
	v_cmp_lt_f32_e32 vcc, s74, v3
	s_cmp_lg_u64 vcc, 0
	s_cselect_b64 s[2:3], -1, 0
	s_cbranch_vccz .LBB0_879
	v_and_b32_e32 v124, 64, v212
	v_xor_b32_e32 v3, 16, v212
	v_add_u32_e32 v124, 64, v124
	v_cmp_lt_i32_e32 vcc, v3, v124
	v_xor_b32_e32 v125, 32, v212
	s_nop 0
	v_cndmask_b32_e32 v3, v212, v3, vcc
	v_lshlrev_b32_e32 v3, 2, v3
	ds_bpermute_b32 v126, v3, v0
	ds_bpermute_b32 v3, v3, v2
	v_cmp_lt_i32_e32 vcc, v125, v124
	v_max_f32_e32 v2, v2, v2
	v_max_f32_e32 v0, v0, v0
	v_cndmask_b32_e32 v124, v212, v125, vcc
	s_waitcnt lgkmcnt(0)
	v_max_f32_e32 v3, v3, v3
	v_lshlrev_b32_e32 v124, 2, v124
	v_max_f32_e32 v125, v126, v126
	v_max_f32_e32 v2, v2, v3
	v_max_f32_e32 v0, v0, v125
	ds_bpermute_b32 v3, v124, v2
	ds_bpermute_b32 v125, v124, v0
	s_waitcnt lgkmcnt(1)
	v_max_f32_e32 v3, v3, v3
	s_waitcnt lgkmcnt(0)
	v_max_f32_e32 v124, v125, v125
	v_max_f32_e32 v2, v2, v3
	v_max_f32_e32 v0, v0, v124
	v_cmp_lt_f32_e32 vcc, s74, v2
	s_nop 1
	v_cndmask_b32_e32 v3, 0, v2, vcc
	v_cmp_lt_f32_e32 vcc, s74, v0
	v_exp_f32_e64 v201, -v3
	v_sub_f32_e32 v108, v108, v3
	v_cndmask_b32_e32 v2, 0, v0, vcc
	v_exp_f32_e64 v200, -v2
	v_sub_f32_e32 v128, v128, v2
	v_sub_f32_e32 v129, v129, v2
	v_sub_f32_e32 v130, v130, v2
	v_sub_f32_e32 v131, v131, v2
	v_sub_f32_e32 v36, v36, v2
	v_sub_f32_e32 v37, v37, v2
	v_sub_f32_e32 v38, v38, v2
	v_sub_f32_e32 v39, v39, v2
	v_sub_f32_e32 v120, v120, v2
	v_sub_f32_e32 v121, v121, v2
	v_sub_f32_e32 v122, v122, v2
	v_sub_f32_e32 v123, v123, v2
	v_sub_f32_e32 v40, v40, v2
	v_sub_f32_e32 v41, v41, v2
	v_sub_f32_e32 v42, v42, v2
	v_sub_f32_e32 v43, v43, v2
	v_pk_add_f32 v[196:197], v[196:197], v[2:3]
	v_sub_f32_e32 v109, v109, v3
	v_sub_f32_e32 v110, v110, v3
	v_sub_f32_e32 v111, v111, v3
	v_sub_f32_e32 v60, v60, v3
	v_sub_f32_e32 v61, v61, v3
	v_sub_f32_e32 v62, v62, v3
	v_sub_f32_e32 v63, v63, v3
	v_sub_f32_e32 v64, v64, v3
	v_sub_f32_e32 v65, v65, v3
	v_sub_f32_e32 v66, v66, v3
	v_sub_f32_e32 v67, v67, v3
	v_sub_f32_e32 v84, v84, v3
	v_sub_f32_e32 v85, v85, v3
	v_sub_f32_e32 v86, v86, v3
	v_sub_f32_e32 v87, v87, v3
	v_pk_mul_f32 v[198:199], v[198:199], v[200:201]
.LBB0_879:
	ds_read_b64_tr_b16 v[124:125], v215 offset:53248
	ds_read_b64_tr_b16 v[100:101], v215 offset:53280
	ds_read_b64_tr_b16 v[116:117], v215 offset:53312
	ds_read_b64_tr_b16 v[96:97], v215 offset:53344
	ds_read_b64_tr_b16 v[126:127], v215 offset:57856
	ds_read_b64_tr_b16 v[102:103], v215 offset:57888
	ds_read_b64_tr_b16 v[118:119], v215 offset:57920
	ds_read_b64_tr_b16 v[98:99], v215 offset:57952
	v_exp_f32_e32 v2, v128
	s_waitcnt lgkmcnt(3)
	v_mfma_f32_16x16x32_bf16 v[104:107], v[44:47], v[124:127], v[144:147]
	s_nop 2
	v_exp_f32_e32 v144, v129
	v_mfma_f32_16x16x32_bf16 v[124:127], v[92:95], v[124:127], v[140:143]
	s_nop 2
	v_exp_f32_e32 v140, v130
	s_waitcnt lgkmcnt(2)
	v_mfma_f32_16x16x32_bf16 v[148:151], v[44:47], v[100:103], v[148:151]
	v_exp_f32_e32 v142, v131
	v_mfma_f32_16x16x32_bf16 v[100:103], v[92:95], v[100:103], v[136:139]
	s_nop 2
	v_exp_f32_e32 v136, v36
	s_waitcnt lgkmcnt(1)
	v_mfma_f32_16x16x32_bf16 v[156:159], v[44:47], v[116:119], v[156:159]
	v_exp_f32_e32 v138, v37
	v_mfma_f32_16x16x32_bf16 v[76:79], v[92:95], v[116:119], v[152:155]
	s_nop 2
	v_exp_f32_e32 v152, v38
	s_waitcnt lgkmcnt(0)
	v_mfma_f32_16x16x32_bf16 v[164:167], v[44:47], v[96:99], v[164:167]
	v_exp_f32_e32 v154, v39
	v_mfma_f32_16x16x32_bf16 v[96:99], v[92:95], v[96:99], v[160:163]
	ds_read_b64_tr_b16 v[128:129], v215 offset:53376
	ds_read_b64_tr_b16 v[116:117], v215 offset:53408
	ds_read_b64_tr_b16 v[88:89], v215 offset:53440
	ds_read_b64_tr_b16 v[80:81], v215 offset:53472
	ds_read_b64_tr_b16 v[130:131], v215 offset:57984
	ds_read_b64_tr_b16 v[118:119], v215 offset:58016
	ds_read_b64_tr_b16 v[90:91], v215 offset:58048
	ds_read_b64_tr_b16 v[82:83], v215 offset:58080
	v_cvt_pk_bf16_f32 v36, v2, v144
	v_cvt_pk_bf16_f32 v37, v140, v142
	v_cvt_pk_bf16_f32 v38, v136, v138
	v_cvt_pk_bf16_f32 v39, v152, v154
	v_exp_f32_e32 v160, v120
	s_waitcnt lgkmcnt(3)
	v_mfma_f32_16x16x32_bf16 v[52:55], v[44:47], v[128:131], v[172:175]
	s_nop 2
	v_exp_f32_e32 v172, v121
	v_mfma_f32_16x16x32_bf16 v[68:71], v[92:95], v[128:131], v[168:171]
	s_nop 2
	v_exp_f32_e32 v168, v122
	s_waitcnt lgkmcnt(2)
	v_mfma_f32_16x16x32_bf16 v[176:179], v[44:47], v[116:119], v[176:179]
	v_exp_f32_e32 v170, v123
	v_mfma_f32_16x16x32_bf16 v[48:51], v[92:95], v[116:119], v[132:135]
	s_nop 2
	v_exp_f32_e32 v132, v40
	s_waitcnt lgkmcnt(1)
	v_mfma_f32_16x16x32_bf16 v[184:187], v[44:47], v[88:91], v[184:187]
	v_exp_f32_e32 v134, v41
	v_mfma_f32_16x16x32_bf16 v[56:59], v[92:95], v[88:91], v[180:183]
	s_nop 2
	v_exp_f32_e32 v180, v42
	s_waitcnt lgkmcnt(0)
	v_mfma_f32_16x16x32_bf16 v[192:195], v[44:47], v[80:83], v[192:195]
	v_exp_f32_e32 v182, v43
	v_mfma_f32_16x16x32_bf16 v[188:191], v[92:95], v[80:83], v[188:191]
	ds_read_b64_tr_b16 v[120:121], v215 offset:62464
	ds_read_b64_tr_b16 v[116:117], v215 offset:62496
	ds_read_b64_tr_b16 v[88:89], v215 offset:62528
	ds_read_b64_tr_b16 v[80:81], v215 offset:62560
	ds_read_b64_tr_b16 v[122:123], v216 offset:13824
	ds_read_b64_tr_b16 v[118:119], v216 offset:13856
	ds_read_b64_tr_b16 v[90:91], v216 offset:13888
	ds_read_b64_tr_b16 v[82:83], v216 offset:13920
	v_cvt_pk_bf16_f32 v40, v160, v172
	v_cvt_pk_bf16_f32 v41, v168, v170
	v_cvt_pk_bf16_f32 v42, v132, v134
	v_cvt_pk_bf16_f32 v43, v180, v182
	v_exp_f32_e32 v3, v108
	s_waitcnt lgkmcnt(3)
	v_mfma_f32_16x16x32_bf16 v[128:131], v[72:75], v[120:123], v[104:107]
	v_exp_f32_e32 v145, v109
	v_mfma_f32_16x16x32_bf16 v[120:123], v[112:115], v[120:123], v[124:127]
	v_exp_f32_e32 v141, v110
	s_waitcnt lgkmcnt(2)
	v_mfma_f32_16x16x32_bf16 v[124:127], v[72:75], v[116:119], v[148:151]
	v_exp_f32_e32 v143, v111
	v_mfma_f32_16x16x32_bf16 v[108:111], v[112:115], v[116:119], v[100:103]
	v_exp_f32_e32 v137, v60
	s_waitcnt lgkmcnt(1)
	v_mfma_f32_16x16x32_bf16 v[116:119], v[72:75], v[88:91], v[156:159]
	v_exp_f32_e32 v139, v61
	v_mfma_f32_16x16x32_bf16 v[100:103], v[112:115], v[88:91], v[76:79]
	v_exp_f32_e32 v153, v62
	s_waitcnt lgkmcnt(0)
	v_mfma_f32_16x16x32_bf16 v[104:107], v[72:75], v[80:83], v[164:167]
	v_exp_f32_e32 v155, v63
	v_mfma_f32_16x16x32_bf16 v[96:99], v[112:115], v[80:83], v[96:99]
	s_nop 0
	ds_read_b64_tr_b16 v[164:165], v215 offset:62592
	ds_read_b64_tr_b16 v[156:157], v215 offset:62624
	ds_read_b64_tr_b16 v[148:149], v215 offset:62656
	ds_read_b64_tr_b16 v[218:219], v215 offset:62688
	ds_read_b64_tr_b16 v[166:167], v216 offset:13952
	ds_read_b64_tr_b16 v[158:159], v216 offset:13984
	ds_read_b64_tr_b16 v[150:151], v216 offset:14016
	ds_read_b64_tr_b16 v[220:221], v216 offset:14048
	v_cvt_pk_bf16_f32 v60, v3, v145
	v_cvt_pk_bf16_f32 v61, v141, v143
	v_cvt_pk_bf16_f32 v62, v137, v139
	v_cvt_pk_bf16_f32 v63, v153, v155
	v_exp_f32_e32 v161, v64
	s_waitcnt lgkmcnt(3)
	v_mfma_f32_16x16x32_bf16 v[88:91], v[72:75], v[164:167], v[52:55]
	v_exp_f32_e32 v173, v65
	v_mfma_f32_16x16x32_bf16 v[76:79], v[112:115], v[164:167], v[68:71]
	v_exp_f32_e32 v169, v66
	s_waitcnt lgkmcnt(2)
	v_mfma_f32_16x16x32_bf16 v[80:83], v[72:75], v[156:159], v[176:179]
	v_exp_f32_e32 v171, v67
	v_mfma_f32_16x16x32_bf16 v[64:67], v[112:115], v[156:159], v[48:51]
	v_exp_f32_e32 v133, v84
	s_waitcnt lgkmcnt(1)
	v_mfma_f32_16x16x32_bf16 v[68:71], v[72:75], v[148:151], v[184:187]
	v_exp_f32_e32 v135, v85
	v_mfma_f32_16x16x32_bf16 v[52:55], v[112:115], v[148:151], v[56:59]
	v_exp_f32_e32 v181, v86
	s_waitcnt lgkmcnt(0)
	v_mfma_f32_16x16x32_bf16 v[56:59], v[72:75], v[218:221], v[192:195]
	v_exp_f32_e32 v183, v87
	v_mfma_f32_16x16x32_bf16 v[48:51], v[112:115], v[218:221], v[188:191]
	v_cvt_pk_bf16_f32 v84, v161, v173
	v_cvt_pk_bf16_f32 v85, v169, v171
	v_cvt_pk_bf16_f32 v86, v133, v135
	v_cvt_pk_bf16_f32 v87, v181, v183
	s_andn2_b64 vcc, exec, s[2:3]
	s_cbranch_vccnz .LBB0_881
	v_mov_b32_e32 v0, v210
	s_nop 0
	v_lshlrev_b32_e32 v0, 2, v0
	v_and_b32_e32 v0, 60, v0
	v_and_or_b32 v0, v212, 64, v0
	v_lshlrev_b32_e32 v0, 2, v0
	ds_bpermute_b32 v188, v0, v200
	ds_bpermute_b32 v190, v0, v200 offset:8
	ds_bpermute_b32 v191, v0, v200 offset:12
	ds_bpermute_b32 v189, v0, v200 offset:4
	ds_bpermute_b32 v192, v0, v201
	ds_bpermute_b32 v194, v0, v201 offset:8
	ds_bpermute_b32 v195, v0, v201 offset:12
	ds_bpermute_b32 v193, v0, v201 offset:4
	s_waitcnt lgkmcnt(5)
	v_pk_mul_f32 v[130:131], v[130:131], v[190:191]
	s_waitcnt lgkmcnt(4)
	v_pk_mul_f32 v[128:129], v[128:129], v[188:189]
	v_pk_mul_f32 v[126:127], v[126:127], v[190:191]
	v_pk_mul_f32 v[124:125], v[124:125], v[188:189]
	v_pk_mul_f32 v[118:119], v[118:119], v[190:191]
	v_pk_mul_f32 v[116:117], v[116:117], v[188:189]
	v_pk_mul_f32 v[106:107], v[106:107], v[190:191]
	v_pk_mul_f32 v[104:105], v[104:105], v[188:189]
	v_pk_mul_f32 v[90:91], v[90:91], v[190:191]
	v_pk_mul_f32 v[88:89], v[88:89], v[188:189]
	v_pk_mul_f32 v[82:83], v[82:83], v[190:191]
	v_pk_mul_f32 v[80:81], v[80:81], v[188:189]
	v_pk_mul_f32 v[70:71], v[70:71], v[190:191]
	v_pk_mul_f32 v[68:69], v[68:69], v[188:189]
	v_pk_mul_f32 v[58:59], v[58:59], v[190:191]
	v_pk_mul_f32 v[56:57], v[56:57], v[188:189]
	s_waitcnt lgkmcnt(1)
	v_pk_mul_f32 v[122:123], v[122:123], v[194:195]
	s_waitcnt lgkmcnt(0)
	v_pk_mul_f32 v[120:121], v[120:121], v[192:193]
	v_pk_mul_f32 v[110:111], v[110:111], v[194:195]
	v_pk_mul_f32 v[108:109], v[108:109], v[192:193]
	v_pk_mul_f32 v[102:103], v[102:103], v[194:195]
	v_pk_mul_f32 v[100:101], v[100:101], v[192:193]
	v_pk_mul_f32 v[98:99], v[98:99], v[194:195]
	v_pk_mul_f32 v[96:97], v[96:97], v[192:193]
	v_pk_mul_f32 v[78:79], v[78:79], v[194:195]
	v_pk_mul_f32 v[76:77], v[76:77], v[192:193]
	v_pk_mul_f32 v[66:67], v[66:67], v[194:195]
	v_pk_mul_f32 v[64:65], v[64:65], v[192:193]
	v_pk_mul_f32 v[54:55], v[54:55], v[194:195]
	v_pk_mul_f32 v[52:53], v[52:53], v[192:193]
	v_pk_mul_f32 v[50:51], v[50:51], v[194:195]
	v_pk_mul_f32 v[48:49], v[48:49], v[192:193]
.LBB0_881:
	v_pk_add_f32 v[2:3], v[198:199], v[2:3]
	s_nop 0
	v_pk_add_f32 v[2:3], v[144:145], v[2:3]
	s_nop 0
	v_pk_add_f32 v[2:3], v[140:141], v[2:3]
	s_nop 0
	v_pk_add_f32 v[2:3], v[142:143], v[2:3]
	s_nop 0
	v_pk_add_f32 v[2:3], v[136:137], v[2:3]
	s_nop 0
	v_pk_add_f32 v[2:3], v[138:139], v[2:3]
	s_nop 0
	v_pk_add_f32 v[2:3], v[152:153], v[2:3]
	s_nop 0
	v_pk_add_f32 v[2:3], v[154:155], v[2:3]
	s_nop 0
	v_pk_add_f32 v[2:3], v[160:161], v[2:3]
	s_nop 0
	v_pk_add_f32 v[2:3], v[172:173], v[2:3]
	s_nop 0
	v_pk_add_f32 v[2:3], v[168:169], v[2:3]
	s_nop 0
	v_pk_add_f32 v[2:3], v[170:171], v[2:3]
	s_nop 0
	v_pk_add_f32 v[2:3], v[132:133], v[2:3]
	s_nop 0
	v_pk_add_f32 v[2:3], v[134:135], v[2:3]
	s_nop 0
	v_pk_add_f32 v[2:3], v[180:181], v[2:3]
	s_nop 0
	v_pk_add_f32 v[198:199], v[182:183], v[2:3]
.LBB0_882:
	s_andn2_b64 vcc, exec, s[60:61]
	s_cbranch_vccnz .LBB0_848

.LBB0_920:
	s_cmp_ge_u32 s83, s62
	s_mov_b64 s[0:1], -1
	s_cbranch_scc0 .LBB0_922
	ds_read_b64_tr_b16 v[132:133], v222 offset:17408
	ds_read_b64_tr_b16 v[136:137], v222 offset:17440
	ds_read_b64_tr_b16 v[140:141], v222 offset:17472
	ds_read_b64_tr_b16 v[144:145], v222 offset:17504
	ds_read_b64_tr_b16 v[134:135], v222 offset:22016
	ds_read_b64_tr_b16 v[138:139], v222 offset:22048
	ds_read_b64_tr_b16 v[142:143], v222 offset:22080
	ds_read_b64_tr_b16 v[146:147], v222 offset:22112
	s_waitcnt lgkmcnt(3)
	v_mfma_f32_16x16x32_bf16 v[148:151], v[36:39], v[132:135], v[128:131]
	v_mfma_f32_16x16x32_bf16 v[132:135], v[48:51], v[132:135], v[124:127]
	s_waitcnt lgkmcnt(2)
	v_mfma_f32_16x16x32_bf16 v[152:155], v[36:39], v[136:139], v[120:123]
	v_mfma_f32_16x16x32_bf16 v[136:139], v[48:51], v[136:139], v[116:119]
	s_waitcnt lgkmcnt(1)
	v_mfma_f32_16x16x32_bf16 v[156:159], v[36:39], v[140:143], v[112:115]
	v_mfma_f32_16x16x32_bf16 v[160:163], v[48:51], v[140:143], v[108:111]
	s_waitcnt lgkmcnt(0)
	v_mfma_f32_16x16x32_bf16 v[164:167], v[36:39], v[144:147], v[104:107]
	v_mfma_f32_16x16x32_bf16 v[168:171], v[48:51], v[144:147], v[100:103]
	ds_read_b64_tr_b16 v[140:141], v222 offset:17536
	ds_read_b64_tr_b16 v[144:145], v222 offset:17568
	ds_read_b64_tr_b16 v[172:173], v222 offset:17600
	ds_read_b64_tr_b16 v[176:177], v222 offset:17632
	ds_read_b64_tr_b16 v[142:143], v222 offset:22144
	ds_read_b64_tr_b16 v[146:147], v222 offset:22176
	ds_read_b64_tr_b16 v[174:175], v222 offset:22208
	ds_read_b64_tr_b16 v[178:179], v222 offset:22240
	s_waitcnt lgkmcnt(3)
	v_mfma_f32_16x16x32_bf16 v[180:183], v[36:39], v[140:143], v[92:95]
	v_mfma_f32_16x16x32_bf16 v[184:187], v[48:51], v[140:143], v[84:87]
	s_waitcnt lgkmcnt(2)
	v_mfma_f32_16x16x32_bf16 v[188:191], v[36:39], v[144:147], v[80:83]
	v_mfma_f32_16x16x32_bf16 v[192:195], v[48:51], v[144:147], v[72:75]
	s_waitcnt lgkmcnt(1)
	v_mfma_f32_16x16x32_bf16 v[226:229], v[36:39], v[172:175], v[68:71]
	v_mfma_f32_16x16x32_bf16 v[230:233], v[48:51], v[172:175], v[64:67]
	s_waitcnt lgkmcnt(0)
	v_mfma_f32_16x16x32_bf16 v[234:237], v[36:39], v[176:179], v[60:63]
	v_mfma_f32_16x16x32_bf16 v[238:241], v[48:51], v[176:179], v[52:55]
	ds_read_b64_tr_b16 v[140:141], v222 offset:26624
	ds_read_b64_tr_b16 v[172:173], v222 offset:26656
	ds_read_b64_tr_b16 v[176:177], v222 offset:26688
	ds_read_b64_tr_b16 v[242:243], v222 offset:26720
	ds_read_b64_tr_b16 v[142:143], v222 offset:31232
	ds_read_b64_tr_b16 v[174:175], v222 offset:31264
	ds_read_b64_tr_b16 v[178:179], v222 offset:31296
	ds_read_b64_tr_b16 v[244:245], v222 offset:31328
	s_waitcnt lgkmcnt(3)
	v_mfma_f32_16x16x32_bf16 v[144:147], v[40:43], v[140:143], v[148:151]
	v_mfma_f32_16x16x32_bf16 v[140:143], v[76:79], v[140:143], v[132:135]
	s_waitcnt lgkmcnt(2)
	v_mfma_f32_16x16x32_bf16 v[148:151], v[40:43], v[172:175], v[152:155]
	v_mfma_f32_16x16x32_bf16 v[136:139], v[76:79], v[172:175], v[136:139]
	s_waitcnt lgkmcnt(1)
	v_mfma_f32_16x16x32_bf16 v[156:159], v[40:43], v[176:179], v[156:159]
	v_mfma_f32_16x16x32_bf16 v[152:155], v[76:79], v[176:179], v[160:163]
	s_waitcnt lgkmcnt(0)
	v_mfma_f32_16x16x32_bf16 v[164:167], v[40:43], v[242:245], v[164:167]
	v_mfma_f32_16x16x32_bf16 v[160:163], v[76:79], v[242:245], v[168:171]
	ds_read_b64_tr_b16 v[132:133], v222 offset:26752
	ds_read_b64_tr_b16 v[242:243], v222 offset:26784
	ds_read_b64_tr_b16 v[246:247], v222 offset:26816
	ds_read_b64_tr_b16 v[250:251], v222 offset:26848
	ds_read_b64_tr_b16 v[134:135], v222 offset:31360
	ds_read_b64_tr_b16 v[244:245], v222 offset:31392
	ds_read_b64_tr_b16 v[248:249], v222 offset:31424
	ds_read_b64_tr_b16 v[252:253], v222 offset:31456
	s_waitcnt lgkmcnt(3)
	v_mfma_f32_16x16x32_bf16 v[172:175], v[40:43], v[132:135], v[180:183]
	v_mfma_f32_16x16x32_bf16 v[168:171], v[76:79], v[132:135], v[184:187]
	s_waitcnt lgkmcnt(2)
	v_mfma_f32_16x16x32_bf16 v[176:179], v[40:43], v[242:245], v[188:191]
	v_mfma_f32_16x16x32_bf16 v[132:135], v[76:79], v[242:245], v[192:195]
	s_waitcnt lgkmcnt(1)
	v_mfma_f32_16x16x32_bf16 v[184:187], v[40:43], v[246:249], v[226:229]
	v_mfma_f32_16x16x32_bf16 v[180:183], v[76:79], v[246:249], v[230:233]
	s_waitcnt lgkmcnt(0)
	v_mfma_f32_16x16x32_bf16 v[192:195], v[40:43], v[250:253], v[234:237]
	v_mfma_f32_16x16x32_bf16 v[188:191], v[76:79], v[250:253], v[238:241]
	s_mov_b64 s[0:1], 0
	s_nop 7
	v_mov_b64_e32 v[128:129], v[144:145]
	v_mov_b64_e32 v[120:121], v[148:149]
	v_mov_b64_e32 v[112:113], v[156:157]
	v_mov_b64_e32 v[104:105], v[164:165]
	v_mov_b64_e32 v[92:93], v[172:173]
	v_mov_b64_e32 v[80:81], v[176:177]
	v_mov_b64_e32 v[68:69], v[184:185]
	v_mov_b64_e32 v[60:61], v[192:193]
	v_mov_b64_e32 v[124:125], v[140:141]
	v_mov_b64_e32 v[116:117], v[136:137]
	v_mov_b64_e32 v[108:109], v[152:153]
	v_mov_b64_e32 v[100:101], v[160:161]
	v_mov_b64_e32 v[84:85], v[168:169]
	v_mov_b64_e32 v[72:73], v[132:133]
	v_mov_b64_e32 v[64:65], v[180:181]
	v_mov_b64_e32 v[52:53], v[188:189]
	v_mov_b64_e32 v[130:131], v[146:147]
	v_mov_b64_e32 v[122:123], v[150:151]
	v_mov_b64_e32 v[114:115], v[158:159]
	v_mov_b64_e32 v[106:107], v[166:167]
	v_mov_b64_e32 v[94:95], v[174:175]
	v_mov_b64_e32 v[82:83], v[178:179]
	v_mov_b64_e32 v[70:71], v[186:187]
	v_mov_b64_e32 v[62:63], v[194:195]
	v_mov_b64_e32 v[126:127], v[142:143]
	v_mov_b64_e32 v[118:119], v[138:139]
	v_mov_b64_e32 v[110:111], v[154:155]
	v_mov_b64_e32 v[102:103], v[162:163]
	v_mov_b64_e32 v[86:87], v[170:171]
	v_mov_b64_e32 v[74:75], v[134:135]
	v_mov_b64_e32 v[66:67], v[182:183]
	v_mov_b64_e32 v[54:55], v[190:191]

.LBB0_936:
	s_cmp_ge_u32 s82, s60
	s_mov_b64 s[2:3], -1
	s_cbranch_scc0 .LBB0_938
	ds_read_b64_tr_b16 v[72:73], v222 offset:53248
	ds_read_b64_tr_b16 v[116:117], v222 offset:53280
	ds_read_b64_tr_b16 v[124:125], v222 offset:53312
	ds_read_b64_tr_b16 v[128:129], v222 offset:53344
	ds_read_b64_tr_b16 v[74:75], v222 offset:57856
	ds_read_b64_tr_b16 v[118:119], v222 offset:57888
	ds_read_b64_tr_b16 v[126:127], v222 offset:57920
	ds_read_b64_tr_b16 v[130:131], v222 offset:57952
	s_waitcnt lgkmcnt(3)
	v_mfma_f32_16x16x32_bf16 v[120:123], v[44:47], v[72:75], v[144:147]
	v_mfma_f32_16x16x32_bf16 v[72:75], v[88:91], v[72:75], v[140:143]
	s_waitcnt lgkmcnt(2)
	v_mfma_f32_16x16x32_bf16 v[108:111], v[44:47], v[116:119], v[148:151]
	v_mfma_f32_16x16x32_bf16 v[116:119], v[88:91], v[116:119], v[136:139]
	s_waitcnt lgkmcnt(1)
	v_mfma_f32_16x16x32_bf16 v[112:115], v[44:47], v[124:127], v[156:159]
	v_mfma_f32_16x16x32_bf16 v[100:103], v[88:91], v[124:127], v[152:155]
	s_waitcnt lgkmcnt(0)
	v_mfma_f32_16x16x32_bf16 v[104:107], v[44:47], v[128:131], v[164:167]
	v_mfma_f32_16x16x32_bf16 v[84:87], v[88:91], v[128:131], v[160:163]
	ds_read_b64_tr_b16 v[124:125], v222 offset:53376
	ds_read_b64_tr_b16 v[128:129], v222 offset:53408
	ds_read_b64_tr_b16 v[92:93], v222 offset:53440
	ds_read_b64_tr_b16 v[80:81], v222 offset:53472
	ds_read_b64_tr_b16 v[126:127], v222 offset:57984
	ds_read_b64_tr_b16 v[130:131], v222 offset:58016
	ds_read_b64_tr_b16 v[94:95], v222 offset:58048
	ds_read_b64_tr_b16 v[82:83], v222 offset:58080
	s_waitcnt lgkmcnt(3)
	v_mfma_f32_16x16x32_bf16 v[64:67], v[44:47], v[124:127], v[172:175]
	v_mfma_f32_16x16x32_bf16 v[68:71], v[88:91], v[124:127], v[168:171]
	s_waitcnt lgkmcnt(2)
	v_mfma_f32_16x16x32_bf16 v[52:55], v[44:47], v[128:131], v[176:179]
	v_mfma_f32_16x16x32_bf16 v[60:63], v[88:91], v[128:131], v[132:135]
	s_waitcnt lgkmcnt(1)
	v_mfma_f32_16x16x32_bf16 v[226:229], v[44:47], v[92:95], v[184:187]
	v_mfma_f32_16x16x32_bf16 v[230:233], v[88:91], v[92:95], v[180:183]
	s_waitcnt lgkmcnt(0)
	v_mfma_f32_16x16x32_bf16 v[234:237], v[44:47], v[80:83], v[192:195]
	v_mfma_f32_16x16x32_bf16 v[238:241], v[88:91], v[80:83], v[188:191]
	ds_read_b64_tr_b16 v[124:125], v222 offset:62464
	ds_read_b64_tr_b16 v[92:93], v222 offset:62496
	ds_read_b64_tr_b16 v[80:81], v222 offset:62528
	ds_read_b64_tr_b16 v[242:243], v222 offset:62560
	ds_read_b64_tr_b16 v[126:127], v223 offset:13824
	ds_read_b64_tr_b16 v[94:95], v223 offset:13856
	ds_read_b64_tr_b16 v[82:83], v223 offset:13888
	ds_read_b64_tr_b16 v[244:245], v223 offset:13920
	s_waitcnt lgkmcnt(3)
	v_mfma_f32_16x16x32_bf16 v[128:131], v[56:59], v[124:127], v[120:123]
	v_mfma_f32_16x16x32_bf16 v[124:127], v[96:99], v[124:127], v[72:75]
	s_waitcnt lgkmcnt(2)
	v_mfma_f32_16x16x32_bf16 v[120:123], v[56:59], v[92:95], v[108:111]
	v_mfma_f32_16x16x32_bf16 v[116:119], v[96:99], v[92:95], v[116:119]
	s_waitcnt lgkmcnt(1)
	v_mfma_f32_16x16x32_bf16 v[112:115], v[56:59], v[80:83], v[112:115]
	v_mfma_f32_16x16x32_bf16 v[108:111], v[96:99], v[80:83], v[100:103]
	s_waitcnt lgkmcnt(0)
	v_mfma_f32_16x16x32_bf16 v[104:107], v[56:59], v[242:245], v[104:107]
	v_mfma_f32_16x16x32_bf16 v[100:103], v[96:99], v[242:245], v[84:87]
	ds_read_b64_tr_b16 v[72:73], v222 offset:62592
	ds_read_b64_tr_b16 v[242:243], v222 offset:62624
	ds_read_b64_tr_b16 v[246:247], v222 offset:62656
	ds_read_b64_tr_b16 v[250:251], v222 offset:62688
	ds_read_b64_tr_b16 v[74:75], v223 offset:13952
	ds_read_b64_tr_b16 v[244:245], v223 offset:13984
	ds_read_b64_tr_b16 v[248:249], v223 offset:14016
	ds_read_b64_tr_b16 v[252:253], v223 offset:14048
	s_waitcnt lgkmcnt(3)
	v_mfma_f32_16x16x32_bf16 v[92:95], v[56:59], v[72:75], v[64:67]
	v_mfma_f32_16x16x32_bf16 v[84:87], v[96:99], v[72:75], v[68:71]
	s_waitcnt lgkmcnt(2)
	v_mfma_f32_16x16x32_bf16 v[80:83], v[56:59], v[242:245], v[52:55]
	v_mfma_f32_16x16x32_bf16 v[72:75], v[96:99], v[242:245], v[60:63]
	s_waitcnt lgkmcnt(1)
	v_mfma_f32_16x16x32_bf16 v[68:71], v[56:59], v[246:249], v[226:229]
	v_mfma_f32_16x16x32_bf16 v[64:67], v[96:99], v[246:249], v[230:233]
	s_waitcnt lgkmcnt(0)
	v_mfma_f32_16x16x32_bf16 v[60:63], v[56:59], v[250:253], v[234:237]
	v_mfma_f32_16x16x32_bf16 v[52:55], v[96:99], v[250:253], v[238:241]
	s_mov_b64 s[2:3], 0
.LBB0_938:
	s_andn2_b64 vcc, exec, s[2:3]
	s_cbranch_vccnz .LBB0_948
	ds_read_b128 v[36:39], v221
	ds_read_b128 v[40:43], v221 offset:64
	ds_read_b128 v[48:51], v221 offset:4352
	ds_read_b128 v[76:79], v221 offset:4416
	ds_read_b128 v[72:75], v221 offset:8704
	ds_read_b128 v[120:123], v221 offset:8768
	ds_read_b128 v[116:119], v221 offset:13056
	ds_read_b128 v[108:111], v221 offset:13120
	s_waitcnt lgkmcnt(7)
	v_mfma_f32_16x16x32_bf16 v[124:127], v[36:39], v[8:11], 0
	v_mfma_f32_16x16x32_bf16 v[36:39], v[36:39], v[20:23], 0
	s_waitcnt lgkmcnt(5)
	v_mfma_f32_16x16x32_bf16 v[112:115], v[48:51], v[8:11], 0
	v_mfma_f32_16x16x32_bf16 v[48:51], v[48:51], v[20:23], 0
	s_waitcnt lgkmcnt(3)
	v_mfma_f32_16x16x32_bf16 v[100:103], v[72:75], v[8:11], 0
	v_mfma_f32_16x16x32_bf16 v[72:75], v[72:75], v[20:23], 0
	s_waitcnt lgkmcnt(1)
	v_mfma_f32_16x16x32_bf16 v[104:107], v[116:119], v[8:11], 0
	v_mfma_f32_16x16x32_bf16 v[84:87], v[116:119], v[20:23], 0
	v_mfma_f32_16x16x32_bf16 v[128:131], v[40:43], v[12:15], v[124:127]
	v_mfma_f32_16x16x32_bf16 v[116:119], v[40:43], v[24:27], v[36:39]
	v_mfma_f32_16x16x32_bf16 v[36:39], v[76:79], v[12:15], v[112:115]
	v_mfma_f32_16x16x32_bf16 v[48:51], v[76:79], v[24:27], v[48:51]
	v_mfma_f32_16x16x32_bf16 v[124:127], v[120:123], v[12:15], v[100:103]
	v_mfma_f32_16x16x32_bf16 v[72:75], v[120:123], v[24:27], v[72:75]
	s_waitcnt lgkmcnt(0)
	v_mfma_f32_16x16x32_bf16 v[40:43], v[108:111], v[12:15], v[104:107]
	v_mfma_f32_16x16x32_bf16 v[76:79], v[108:111], v[24:27], v[84:87]
	v_cmp_neq_f32_e32 vcc, 0, v196
	v_cmp_neq_f32_e64 s[2:3], 0, v197
	s_or_b64 vcc, vcc, s[2:3]
	s_cbranch_vccz .LBB0_941
	v_sub_f32_e32 v131, v131, v196
	v_sub_f32_e32 v130, v130, v196
	v_sub_f32_e32 v129, v129, v196
	v_sub_f32_e32 v128, v128, v196
	v_sub_f32_e32 v39, v39, v196
	v_sub_f32_e32 v38, v38, v196
	v_sub_f32_e32 v37, v37, v196
	v_sub_f32_e32 v36, v36, v196
	v_sub_f32_e32 v127, v127, v196
	v_sub_f32_e32 v126, v126, v196
	v_sub_f32_e32 v125, v125, v196
	v_sub_f32_e32 v124, v124, v196
	v_sub_f32_e32 v43, v43, v196
	v_sub_f32_e32 v42, v42, v196
	v_sub_f32_e32 v41, v41, v196
	v_sub_f32_e32 v40, v40, v196
	v_sub_f32_e32 v119, v119, v197
	v_sub_f32_e32 v118, v118, v197
	v_sub_f32_e32 v117, v117, v197
	v_sub_f32_e32 v116, v116, v197
	v_sub_f32_e32 v51, v51, v197
	v_sub_f32_e32 v50, v50, v197
	v_sub_f32_e32 v49, v49, v197
	v_sub_f32_e32 v48, v48, v197
	v_sub_f32_e32 v75, v75, v197
	v_sub_f32_e32 v74, v74, v197
	v_sub_f32_e32 v73, v73, v197
	v_sub_f32_e32 v72, v72, v197
	v_sub_f32_e32 v79, v79, v197
	v_sub_f32_e32 v78, v78, v197
	v_sub_f32_e32 v77, v77, v197
	v_sub_f32_e32 v76, v76, v197
.LBB0_941:
	s_add_i32 s2, s80, 64
	s_cmp_le_i32 s2, s63
	s_cbranch_scc1 .LBB0_943
	v_add_u32_e32 v0, s80, v224
	v_add_u32_e32 v110, 0xc0, v0
	v_max_i32_e32 v3, -1, v110
	v_max_i32_e32 v120, -2, v110
	v_max_i32_e32 v121, -3, v110
	v_max_i32_e32 v122, -16, v110
	v_max_i32_e32 v123, 0xffffffef, v110
	v_max_i32_e32 v108, 0xffffffee, v110
	v_max_i32_e32 v109, 0xffffffed, v110
	v_add_u32_e32 v3, 1, v3
	v_add_u32_e32 v120, 2, v120
	v_add_u32_e32 v121, 3, v121
	v_add_u32_e32 v122, 16, v122
	v_add_u32_e32 v123, 17, v123
	v_add_u32_e32 v108, 18, v108
	v_add_u32_e32 v109, 19, v109
	v_med3_i32 v2, v110, 0, v209
	v_min_u32_e32 v3, 0xff, v3
	v_min_u32_e32 v120, 0xff, v120
	v_min_u32_e32 v121, 0xff, v121
	v_min_u32_e32 v122, 0xff, v122
	v_min_u32_e32 v123, 0xff, v123
	v_min_u32_e32 v108, 0xff, v108
	v_min_u32_e32 v109, 0xff, v109
	v_lshl_add_u32 v2, v2, 2, s71
	v_lshl_add_u32 v3, v3, 2, s71
	v_lshl_add_u32 v120, v120, 2, s71
	v_lshl_add_u32 v121, v121, 2, s71
	v_lshl_add_u32 v122, v122, 2, s71
	v_lshl_add_u32 v123, v123, 2, s71
	v_lshl_add_u32 v108, v108, 2, s71
	v_lshl_add_u32 v109, v109, 2, s71
	ds_read_b32 v2, v2
	ds_read_b32 v3, v3
	ds_read_b32 v120, v120
	ds_read_b32 v121, v121
	ds_read_b32 v122, v122
	ds_read_b32 v123, v123
	ds_read_b32 v108, v108
	ds_read_b32 v109, v109
	s_waitcnt lgkmcnt(4)
	v_pk_add_f32 v[130:131], v[130:131], v[120:121]
	v_pk_add_f32 v[128:129], v[128:129], v[2:3]
	v_max_i32_e32 v2, 0xffffffe0, v110
	v_max_i32_e32 v3, 0xffffffdf, v110
	v_max_i32_e32 v120, 0xffffffde, v110
	v_max_i32_e32 v121, 0xffffffdd, v110
	v_max_i32_e32 v111, 0xffffffd0, v110
	v_max_i32_e32 v112, 0xffffffcf, v110
	v_max_i32_e32 v113, 0xffffffce, v110
	v_add_u32_e32 v2, 32, v2
	v_add_u32_e32 v3, 33, v3
	v_add_u32_e32 v120, 34, v120
	v_add_u32_e32 v121, 35, v121
	v_add_u32_e32 v111, 48, v111
	v_add_u32_e32 v112, 49, v112
	v_add_u32_e32 v113, 50, v113
	v_max_i32_e32 v110, 0xffffffcd, v110
	v_min_u32_e32 v2, 0xff, v2
	v_min_u32_e32 v3, 0xff, v3
	v_min_u32_e32 v120, 0xff, v120
	v_min_u32_e32 v121, 0xff, v121
	v_min_u32_e32 v111, 0xff, v111
	v_min_u32_e32 v112, 0xff, v112
	v_min_u32_e32 v113, 0xff, v113
	v_add_u32_e32 v110, 51, v110
	v_lshl_add_u32 v2, v2, 2, s71
	v_lshl_add_u32 v3, v3, 2, s71
	v_lshl_add_u32 v120, v120, 2, s71
	v_lshl_add_u32 v121, v121, 2, s71
	v_lshl_add_u32 v111, v111, 2, s71
	v_lshl_add_u32 v112, v112, 2, s71
	v_lshl_add_u32 v113, v113, 2, s71
	v_min_u32_e32 v110, 0xff, v110
	v_lshl_add_u32 v114, v110, 2, s71
	ds_read_b32 v2, v2
	ds_read_b32 v3, v3
	ds_read_b32 v120, v120
	ds_read_b32 v121, v121
	ds_read_b32 v110, v111
	ds_read_b32 v111, v112
	ds_read_b32 v112, v113
	ds_read_b32 v113, v114
	v_add_u32_e32 v0, 0xb0, v0
	s_waitcnt lgkmcnt(8)
	v_pk_add_f32 v[38:39], v[38:39], v[108:109]
	v_pk_add_f32 v[36:37], v[36:37], v[122:123]
	s_waitcnt lgkmcnt(4)
	v_pk_add_f32 v[126:127], v[126:127], v[120:121]
	v_pk_add_f32 v[124:125], v[124:125], v[2:3]
	v_max_i32_e32 v3, -1, v0
	v_max_i32_e32 v120, -2, v0
	v_max_i32_e32 v121, -3, v0
	v_max_i32_e32 v122, -16, v0
	v_max_i32_e32 v123, 0xffffffef, v0
	v_max_i32_e32 v108, 0xffffffee, v0
	v_max_i32_e32 v109, 0xffffffed, v0
	v_add_u32_e32 v3, 1, v3
	v_add_u32_e32 v120, 2, v120
	v_add_u32_e32 v121, 3, v121
	v_add_u32_e32 v122, 16, v122
	v_add_u32_e32 v123, 17, v123
	v_add_u32_e32 v108, 18, v108
	v_add_u32_e32 v109, 19, v109
	v_med3_i32 v2, v0, 0, v209
	v_min_u32_e32 v3, 0xff, v3
	v_min_u32_e32 v120, 0xff, v120
	v_min_u32_e32 v121, 0xff, v121
	v_min_u32_e32 v122, 0xff, v122
	v_min_u32_e32 v123, 0xff, v123
	v_min_u32_e32 v108, 0xff, v108
	v_min_u32_e32 v109, 0xff, v109
	v_lshl_add_u32 v2, v2, 2, s71
	v_lshl_add_u32 v3, v3, 2, s71
	v_lshl_add_u32 v120, v120, 2, s71
	v_lshl_add_u32 v121, v121, 2, s71
	v_lshl_add_u32 v122, v122, 2, s71
	v_lshl_add_u32 v123, v123, 2, s71
	v_lshl_add_u32 v108, v108, 2, s71
	v_lshl_add_u32 v109, v109, 2, s71
	ds_read_b32 v2, v2
	ds_read_b32 v3, v3
	ds_read_b32 v120, v120
	ds_read_b32 v121, v121
	ds_read_b32 v122, v122
	ds_read_b32 v123, v123
	ds_read_b32 v108, v108
	ds_read_b32 v109, v109
	s_waitcnt lgkmcnt(8)
	v_pk_add_f32 v[42:43], v[42:43], v[112:113]
	v_pk_add_f32 v[40:41], v[40:41], v[110:111]
	s_waitcnt lgkmcnt(4)
	v_pk_add_f32 v[118:119], v[118:119], v[120:121]
	v_pk_add_f32 v[116:117], v[116:117], v[2:3]
	v_max_i32_e32 v2, 0xffffffe0, v0
	v_max_i32_e32 v3, 0xffffffdf, v0
	v_max_i32_e32 v120, 0xffffffde, v0
	v_max_i32_e32 v121, 0xffffffdd, v0
	v_max_i32_e32 v110, 0xffffffd0, v0
	v_max_i32_e32 v111, 0xffffffcf, v0
	v_max_i32_e32 v112, 0xffffffce, v0
	v_add_u32_e32 v2, 32, v2
	v_add_u32_e32 v3, 33, v3
	v_add_u32_e32 v120, 34, v120
	v_add_u32_e32 v121, 35, v121
	v_add_u32_e32 v110, 48, v110
	v_add_u32_e32 v111, 49, v111
	v_add_u32_e32 v112, 50, v112
	v_max_i32_e32 v0, 0xffffffcd, v0
	v_min_u32_e32 v2, 0xff, v2
	v_min_u32_e32 v3, 0xff, v3
	v_min_u32_e32 v120, 0xff, v120
	v_min_u32_e32 v121, 0xff, v121
	v_min_u32_e32 v110, 0xff, v110
	v_min_u32_e32 v111, 0xff, v111
	v_min_u32_e32 v112, 0xff, v112
	v_add_u32_e32 v0, 51, v0
	v_lshl_add_u32 v2, v2, 2, s71
	v_lshl_add_u32 v3, v3, 2, s71
	v_lshl_add_u32 v120, v120, 2, s71
	v_lshl_add_u32 v121, v121, 2, s71
	v_lshl_add_u32 v110, v110, 2, s71
	v_lshl_add_u32 v111, v111, 2, s71
	v_lshl_add_u32 v112, v112, 2, s71
	v_min_u32_e32 v0, 0xff, v0
	v_lshl_add_u32 v0, v0, 2, s71
	ds_read_b32 v2, v2
	ds_read_b32 v3, v3
	ds_read_b32 v120, v120
	ds_read_b32 v121, v121
	ds_read_b32 v110, v110
	ds_read_b32 v111, v111
	ds_read_b32 v112, v112
	ds_read_b32 v113, v0
	s_waitcnt lgkmcnt(8)
	v_pk_add_f32 v[50:51], v[50:51], v[108:109]
	v_pk_add_f32 v[48:49], v[48:49], v[122:123]
	s_waitcnt lgkmcnt(4)
	v_pk_add_f32 v[74:75], v[74:75], v[120:121]
	v_pk_add_f32 v[72:73], v[72:73], v[2:3]
	s_waitcnt lgkmcnt(0)
	v_pk_add_f32 v[78:79], v[78:79], v[112:113]
	v_pk_add_f32 v[76:77], v[76:77], v[110:111]
.LBB0_943:
	v_max_f32_e32 v0, v129, v129
	v_max_f32_e32 v2, v128, v128
	v_max_f32_e32 v0, v2, v0
	v_max3_f32 v2, v131, v36, v37
	v_max3_f32 v0, v0, v130, v38
	v_max3_f32 v2, v2, v124, v125
	v_max3_f32 v0, v0, v39, v126
	v_max3_f32 v2, v2, v40, v41
	v_max3_f32 v0, v0, v127, v42
	v_max3_f32 v0, v0, v43, v2
	v_max_f32_e32 v2, v117, v117
	v_max_f32_e32 v3, v116, v116
	v_max_f32_e32 v2, v3, v2
	v_max3_f32 v3, v119, v48, v49
	v_max3_f32 v2, v2, v118, v50
	v_max3_f32 v3, v3, v72, v73
	v_max3_f32 v2, v2, v51, v74
	v_max3_f32 v3, v3, v76, v77
	v_max3_f32 v2, v2, v75, v78
	v_max3_f32 v2, v2, v79, v3
	v_max_f32_e32 v3, v0, v2
	v_cmp_lt_f32_e32 vcc, s74, v3
	s_cmp_lg_u64 vcc, 0
	s_cselect_b64 s[2:3], -1, 0
	s_cbranch_vccz .LBB0_945
	ds_bpermute_b32 v120, v217, v2
	ds_bpermute_b32 v3, v217, v0
	v_max_f32_e32 v2, v2, v2
	v_max_f32_e32 v0, v0, v0
	s_waitcnt lgkmcnt(1)
	v_max_f32_e32 v120, v120, v120
	s_waitcnt lgkmcnt(0)
	v_max_f32_e32 v3, v3, v3
	v_max_f32_e32 v2, v2, v120
	v_max_f32_e32 v0, v0, v3
	ds_bpermute_b32 v120, v216, v2
	ds_bpermute_b32 v3, v216, v0
	s_waitcnt lgkmcnt(1)
	v_max_f32_e32 v120, v120, v120
	s_waitcnt lgkmcnt(0)
	v_max_f32_e32 v3, v3, v3
	v_max_f32_e32 v2, v2, v120
	v_max_f32_e32 v0, v0, v3
	v_cmp_lt_f32_e32 vcc, s74, v2
	s_nop 1
	v_cndmask_b32_e32 v3, 0, v2, vcc
	v_cmp_lt_f32_e32 vcc, s74, v0
	v_exp_f32_e64 v199, -v3
	v_sub_f32_e32 v116, v116, v3
	v_cndmask_b32_e32 v2, 0, v0, vcc
	v_exp_f32_e64 v198, -v2
	v_sub_f32_e32 v128, v128, v2
	v_sub_f32_e32 v129, v129, v2
	v_sub_f32_e32 v130, v130, v2
	v_sub_f32_e32 v131, v131, v2
	v_sub_f32_e32 v36, v36, v2
	v_sub_f32_e32 v37, v37, v2
	v_sub_f32_e32 v38, v38, v2
	v_sub_f32_e32 v39, v39, v2
	v_sub_f32_e32 v124, v124, v2
	v_sub_f32_e32 v125, v125, v2
	v_sub_f32_e32 v126, v126, v2
	v_sub_f32_e32 v127, v127, v2
	v_sub_f32_e32 v40, v40, v2
	v_sub_f32_e32 v41, v41, v2
	v_sub_f32_e32 v42, v42, v2
	v_sub_f32_e32 v43, v43, v2
	v_pk_add_f32 v[196:197], v[196:197], v[2:3]
	v_sub_f32_e32 v117, v117, v3
	v_sub_f32_e32 v118, v118, v3
	v_sub_f32_e32 v119, v119, v3
	v_sub_f32_e32 v48, v48, v3
	v_sub_f32_e32 v49, v49, v3
	v_sub_f32_e32 v50, v50, v3
	v_sub_f32_e32 v51, v51, v3
	v_sub_f32_e32 v72, v72, v3
	v_sub_f32_e32 v73, v73, v3
	v_sub_f32_e32 v74, v74, v3
	v_sub_f32_e32 v75, v75, v3
	v_sub_f32_e32 v76, v76, v3
	v_sub_f32_e32 v77, v77, v3
	v_sub_f32_e32 v78, v78, v3
	v_sub_f32_e32 v79, v79, v3
	v_pk_mul_f32 v[200:201], v[200:201], v[198:199]
.LBB0_945:
	ds_read_b64_tr_b16 v[120:121], v222 offset:53248
	ds_read_b64_tr_b16 v[108:109], v222 offset:53280
	ds_read_b64_tr_b16 v[112:113], v222 offset:53312
	ds_read_b64_tr_b16 v[100:101], v222 offset:53344
	ds_read_b64_tr_b16 v[122:123], v222 offset:57856
	ds_read_b64_tr_b16 v[110:111], v222 offset:57888
	ds_read_b64_tr_b16 v[114:115], v222 offset:57920
	ds_read_b64_tr_b16 v[102:103], v222 offset:57952
	v_exp_f32_e32 v2, v128
	s_waitcnt lgkmcnt(3)
	v_mfma_f32_16x16x32_bf16 v[104:107], v[44:47], v[120:123], v[144:147]
	s_nop 2
	v_exp_f32_e32 v144, v129
	v_mfma_f32_16x16x32_bf16 v[120:123], v[88:91], v[120:123], v[140:143]
	s_nop 2
	v_exp_f32_e32 v140, v130
	s_waitcnt lgkmcnt(2)
	v_mfma_f32_16x16x32_bf16 v[84:87], v[44:47], v[108:111], v[148:151]
	s_nop 2
	v_exp_f32_e32 v148, v131
	v_mfma_f32_16x16x32_bf16 v[108:111], v[88:91], v[108:111], v[136:139]
	s_nop 2
	v_exp_f32_e32 v136, v36
	s_waitcnt lgkmcnt(1)
	v_mfma_f32_16x16x32_bf16 v[92:95], v[44:47], v[112:115], v[156:159]
	s_nop 2
	v_exp_f32_e32 v156, v37
	v_mfma_f32_16x16x32_bf16 v[80:83], v[88:91], v[112:115], v[152:155]
	s_nop 2
	v_exp_f32_e32 v152, v38
	s_waitcnt lgkmcnt(0)
	v_mfma_f32_16x16x32_bf16 v[64:67], v[44:47], v[100:103], v[164:167]
	s_nop 2
	v_exp_f32_e32 v164, v39
	v_mfma_f32_16x16x32_bf16 v[100:103], v[88:91], v[100:103], v[160:163]
	ds_read_b64_tr_b16 v[128:129], v222 offset:53376
	ds_read_b64_tr_b16 v[112:113], v222 offset:53408
	ds_read_b64_tr_b16 v[68:69], v222 offset:53440
	ds_read_b64_tr_b16 v[52:53], v222 offset:53472
	ds_read_b64_tr_b16 v[130:131], v222 offset:57984
	ds_read_b64_tr_b16 v[114:115], v222 offset:58016
	ds_read_b64_tr_b16 v[70:71], v222 offset:58048
	ds_read_b64_tr_b16 v[54:55], v222 offset:58080
	v_cvt_pk_bf16_f32 v36, v2, v144
	v_cvt_pk_bf16_f32 v37, v140, v148
	v_cvt_pk_bf16_f32 v38, v136, v156
	v_cvt_pk_bf16_f32 v39, v152, v164
	v_exp_f32_e32 v160, v124
	s_waitcnt lgkmcnt(3)
	v_mfma_f32_16x16x32_bf16 v[60:63], v[44:47], v[128:131], v[172:175]
	s_nop 2
	v_exp_f32_e32 v172, v125
	v_mfma_f32_16x16x32_bf16 v[226:229], v[88:91], v[128:131], v[168:171]
	s_nop 2
	v_exp_f32_e32 v168, v126
	s_waitcnt lgkmcnt(2)
	v_mfma_f32_16x16x32_bf16 v[230:233], v[44:47], v[112:115], v[176:179]
	s_nop 2
	v_exp_f32_e32 v176, v127
	v_mfma_f32_16x16x32_bf16 v[234:237], v[88:91], v[112:115], v[132:135]
	s_nop 2
	v_exp_f32_e32 v132, v40
	s_waitcnt lgkmcnt(1)
	v_mfma_f32_16x16x32_bf16 v[238:241], v[44:47], v[68:71], v[184:187]
	s_nop 2
	v_exp_f32_e32 v184, v41
	v_mfma_f32_16x16x32_bf16 v[242:245], v[88:91], v[68:71], v[180:183]
	s_nop 2
	v_exp_f32_e32 v180, v42
	s_waitcnt lgkmcnt(0)
	v_mfma_f32_16x16x32_bf16 v[246:249], v[44:47], v[52:55], v[192:195]
	s_nop 2
	v_exp_f32_e32 v192, v43
	v_mfma_f32_16x16x32_bf16 v[188:191], v[88:91], v[52:55], v[188:191]
	ds_read_b64_tr_b16 v[124:125], v222 offset:62464
	ds_read_b64_tr_b16 v[112:113], v222 offset:62496
	ds_read_b64_tr_b16 v[68:69], v222 offset:62528
	ds_read_b64_tr_b16 v[52:53], v222 offset:62560
	ds_read_b64_tr_b16 v[126:127], v223 offset:13824
	ds_read_b64_tr_b16 v[114:115], v223 offset:13856
	ds_read_b64_tr_b16 v[70:71], v223 offset:13888
	ds_read_b64_tr_b16 v[54:55], v223 offset:13920
	v_cvt_pk_bf16_f32 v40, v160, v172
	v_cvt_pk_bf16_f32 v41, v168, v176
	v_cvt_pk_bf16_f32 v42, v132, v184
	v_cvt_pk_bf16_f32 v43, v180, v192
	v_exp_f32_e32 v3, v116
	s_waitcnt lgkmcnt(3)
	v_mfma_f32_16x16x32_bf16 v[128:131], v[56:59], v[124:127], v[104:107]
	v_exp_f32_e32 v145, v117
	v_mfma_f32_16x16x32_bf16 v[124:127], v[96:99], v[124:127], v[120:123]
	v_exp_f32_e32 v141, v118
	s_waitcnt lgkmcnt(2)
	v_mfma_f32_16x16x32_bf16 v[120:123], v[56:59], v[112:115], v[84:87]
	v_exp_f32_e32 v149, v119
	v_mfma_f32_16x16x32_bf16 v[116:119], v[96:99], v[112:115], v[108:111]
	v_exp_f32_e32 v137, v48
	s_waitcnt lgkmcnt(1)
	v_mfma_f32_16x16x32_bf16 v[112:115], v[56:59], v[68:71], v[92:95]
	v_exp_f32_e32 v157, v49
	v_mfma_f32_16x16x32_bf16 v[108:111], v[96:99], v[68:71], v[80:83]
	v_exp_f32_e32 v153, v50
	s_waitcnt lgkmcnt(0)
	v_mfma_f32_16x16x32_bf16 v[104:107], v[56:59], v[52:55], v[64:67]
	v_exp_f32_e32 v165, v51
	v_mfma_f32_16x16x32_bf16 v[100:103], v[96:99], v[52:55], v[100:103]
	ds_read_b64_tr_b16 v[84:85], v222 offset:62592
	ds_read_b64_tr_b16 v[64:65], v222 offset:62624
	ds_read_b64_tr_b16 v[52:53], v222 offset:62656
	ds_read_b64_tr_b16 v[250:251], v222 offset:62688
	ds_read_b64_tr_b16 v[86:87], v223 offset:13952
	ds_read_b64_tr_b16 v[66:67], v223 offset:13984
	ds_read_b64_tr_b16 v[54:55], v223 offset:14016
	ds_read_b64_tr_b16 v[252:253], v223 offset:14048
	v_cvt_pk_bf16_f32 v48, v3, v145
	v_cvt_pk_bf16_f32 v49, v141, v149
	v_cvt_pk_bf16_f32 v50, v137, v157
	v_cvt_pk_bf16_f32 v51, v153, v165
	v_exp_f32_e32 v161, v72
	s_waitcnt lgkmcnt(3)
	v_mfma_f32_16x16x32_bf16 v[92:95], v[56:59], v[84:87], v[60:63]
	v_exp_f32_e32 v173, v73
	v_mfma_f32_16x16x32_bf16 v[84:87], v[96:99], v[84:87], v[226:229]
	v_exp_f32_e32 v169, v74
	s_waitcnt lgkmcnt(2)
	v_mfma_f32_16x16x32_bf16 v[80:83], v[56:59], v[64:67], v[230:233]
	v_exp_f32_e32 v177, v75
	v_mfma_f32_16x16x32_bf16 v[72:75], v[96:99], v[64:67], v[234:237]
	v_exp_f32_e32 v133, v76
	s_waitcnt lgkmcnt(1)
	v_mfma_f32_16x16x32_bf16 v[68:71], v[56:59], v[52:55], v[238:241]
	v_exp_f32_e32 v185, v77
	v_mfma_f32_16x16x32_bf16 v[64:67], v[96:99], v[52:55], v[242:245]
	v_exp_f32_e32 v181, v78
	s_waitcnt lgkmcnt(0)
	v_mfma_f32_16x16x32_bf16 v[60:63], v[56:59], v[250:253], v[246:249]
	v_exp_f32_e32 v193, v79
	v_mfma_f32_16x16x32_bf16 v[52:55], v[96:99], v[250:253], v[188:191]
	v_cvt_pk_bf16_f32 v76, v161, v173
	v_cvt_pk_bf16_f32 v77, v169, v177
	v_cvt_pk_bf16_f32 v78, v133, v185
	v_cvt_pk_bf16_f32 v79, v181, v193
	s_andn2_b64 vcc, exec, s[2:3]
	s_cbranch_vccnz .LBB0_947
	v_mov_b32_e32 v0, v218
	s_nop 0
	v_lshlrev_b32_e32 v0, 2, v0
	v_and_or_b32 v0, v0, 60, v215
	v_lshlrev_b32_e32 v0, 2, v0
	ds_bpermute_b32 v188, v0, v198
	ds_bpermute_b32 v190, v0, v198 offset:8
	ds_bpermute_b32 v191, v0, v198 offset:12
	ds_bpermute_b32 v189, v0, v198 offset:4
	ds_bpermute_b32 v194, v0, v199
	ds_bpermute_b32 v182, v0, v199 offset:8
	ds_bpermute_b32 v183, v0, v199 offset:12
	ds_bpermute_b32 v195, v0, v199 offset:4
	s_waitcnt lgkmcnt(5)
	v_pk_mul_f32 v[130:131], v[130:131], v[190:191]
	s_waitcnt lgkmcnt(4)
	v_pk_mul_f32 v[128:129], v[128:129], v[188:189]
	v_pk_mul_f32 v[122:123], v[122:123], v[190:191]
	v_pk_mul_f32 v[120:121], v[120:121], v[188:189]
	v_pk_mul_f32 v[114:115], v[114:115], v[190:191]
	v_pk_mul_f32 v[112:113], v[112:113], v[188:189]
	v_pk_mul_f32 v[106:107], v[106:107], v[190:191]
	v_pk_mul_f32 v[104:105], v[104:105], v[188:189]
	v_pk_mul_f32 v[94:95], v[94:95], v[190:191]
	v_pk_mul_f32 v[92:93], v[92:93], v[188:189]
	v_pk_mul_f32 v[82:83], v[82:83], v[190:191]
	v_pk_mul_f32 v[80:81], v[80:81], v[188:189]
	v_pk_mul_f32 v[70:71], v[70:71], v[190:191]
	v_pk_mul_f32 v[68:69], v[68:69], v[188:189]
	v_pk_mul_f32 v[62:63], v[62:63], v[190:191]
	v_pk_mul_f32 v[60:61], v[60:61], v[188:189]
	s_waitcnt lgkmcnt(1)
	v_pk_mul_f32 v[126:127], v[126:127], v[182:183]
	s_waitcnt lgkmcnt(0)
	v_pk_mul_f32 v[124:125], v[124:125], v[194:195]
	v_pk_mul_f32 v[118:119], v[118:119], v[182:183]
	v_pk_mul_f32 v[116:117], v[116:117], v[194:195]
	v_pk_mul_f32 v[110:111], v[110:111], v[182:183]
	v_pk_mul_f32 v[108:109], v[108:109], v[194:195]
	v_pk_mul_f32 v[102:103], v[102:103], v[182:183]
	v_pk_mul_f32 v[100:101], v[100:101], v[194:195]
	v_pk_mul_f32 v[86:87], v[86:87], v[182:183]
	v_pk_mul_f32 v[84:85], v[84:85], v[194:195]
	v_pk_mul_f32 v[74:75], v[74:75], v[182:183]
	v_pk_mul_f32 v[72:73], v[72:73], v[194:195]
	v_pk_mul_f32 v[66:67], v[66:67], v[182:183]
	v_pk_mul_f32 v[64:65], v[64:65], v[194:195]
	v_pk_mul_f32 v[54:55], v[54:55], v[182:183]
	v_pk_mul_f32 v[52:53], v[52:53], v[194:195]
.LBB0_947:
	v_pk_add_f32 v[2:3], v[200:201], v[2:3]
	s_nop 0
	v_pk_add_f32 v[2:3], v[144:145], v[2:3]
	s_nop 0
	v_pk_add_f32 v[2:3], v[140:141], v[2:3]
	s_nop 0
	v_pk_add_f32 v[2:3], v[148:149], v[2:3]
	s_nop 0
	v_pk_add_f32 v[2:3], v[136:137], v[2:3]
	s_nop 0
	v_pk_add_f32 v[2:3], v[156:157], v[2:3]
	s_nop 0
	v_pk_add_f32 v[2:3], v[152:153], v[2:3]
	s_nop 0
	v_pk_add_f32 v[2:3], v[164:165], v[2:3]
	s_nop 0
	v_pk_add_f32 v[2:3], v[160:161], v[2:3]
	s_nop 0
	v_pk_add_f32 v[2:3], v[172:173], v[2:3]
	s_nop 0
	v_pk_add_f32 v[2:3], v[168:169], v[2:3]
	s_nop 0
	v_pk_add_f32 v[2:3], v[176:177], v[2:3]
	s_nop 0
	v_pk_add_f32 v[2:3], v[132:133], v[2:3]
	s_nop 0
	v_pk_add_f32 v[2:3], v[184:185], v[2:3]
	s_nop 0
	v_pk_add_f32 v[2:3], v[180:181], v[2:3]
	s_nop 0
	v_pk_add_f32 v[200:201], v[192:193], v[2:3]
.LBB0_948:
	s_andn2_b64 vcc, exec, s[44:45]
	s_cbranch_vccnz .LBB0_914
